# x copy removed: layer-0 norm and out-proj epilogue read x_prompt/x_sample directly
# speedup vs baseline: 1.0515x; 1.0081x over previous
.LBB0_65:
	s_or_b64 exec, exec, s[8:9]
	v_lshl_add_u32 v0, s58, 8, v162
	s_mov_b32 s3, 0x100000
	s_lshl_b32 s16, s2, 8
	v_cmp_gt_i32_e32 vcc, s3, v0
	v_ashrrev_i32_e32 v1, 31, v0
	s_mov_b64 s[18:19], exec
	s_branch .LBB0_68
	s_load_dwordx4 s[8:11], s[14:15], 0x0
	s_ashr_i32 s17, s16, 31
	v_lshlrev_b64 v[2:3], 4, v[0:1]
	s_lshl_b64 s[20:21], s[16:17], 4
	s_mov_b64 s[22:23], 0
	s_mov_b32 s3, 0xfffff
	v_mov_b32_e32 v4, v0

.LBB0_137:
	s_cmp_gt_i32 s60, 1
	s_cselect_b64 s[2:3], -1, 0
	s_cmp_lt_i32 s61, 1
	s_cselect_b64 s[4:5], -1, 0
	s_or_b64 s[2:3], s[2:3], s[4:5]
	s_and_b64 vcc, exec, s[2:3]
	v_lshrrev_b32_e32 v163, 4, v162
	s_cbranch_vccnz .LBB0_200
	s_mov_b64 s[12:13], s[0:1]
	s_load_dwordx2 s[14:15], s[12:13], 0xe0
	s_load_dword s2, s[0:1], 0xf0
	v_and_b32_e32 v0, 60, v163
	s_add_u32 s10, s0, 0xf0
	v_lshl_add_u32 v40, s58, 4, v0
	s_movk_i32 s3, 0x2000
	s_addc_u32 s11, s1, 0
	v_cmp_gt_i32_e32 vcc, s3, v40
	s_and_saveexec_b64 s[16:17], vcc
	s_cbranch_execz .LBB0_141
	v_mbcnt_lo_u32_b32 v1, -1, 0
	v_mbcnt_hi_u32_b32 v1, -1, v1
	v_and_b32_e32 v2, 64, v1
	v_add_u32_e32 v3, 64, v2
	v_xor_b32_e32 v5, 32, v1
	v_cmp_lt_i32_e32 vcc, v5, v3
	s_load_dwordx2 s[6:7], s[12:13], 0x50
	s_load_dwordx4 s[64:67], s[0:1], 0x0
	s_waitcnt lgkmcnt(0)
	s_sub_u32 s66, s66, 0x1000000
	s_subb_u32 s67, s67, 0
	s_sub_u32 s64, s64, 0x6b7a100
	s_subb_u32 s65, s65, 0
	s_sub_u32 s66, s66, 0x6b7a100
	s_subb_u32 s67, s67, 0
	s_movk_i32 s68, 0x1000
	s_add_u32 s4, s14, 0x6b02000
	v_cndmask_b32_e32 v5, v1, v5, vcc
	v_lshlrev_b32_e32 v68, 2, v5
	v_xor_b32_e32 v5, 16, v1
	v_cmp_lt_i32_e32 vcc, v5, v3
	s_addc_u32 s5, s15, 0
	v_and_b32_e32 v0, 63, v162
	v_cndmask_b32_e32 v5, v1, v5, vcc
	v_lshlrev_b32_e32 v69, 2, v5
	v_xor_b32_e32 v5, 8, v1
	v_cmp_lt_i32_e32 vcc, v5, v3
	s_lshl_b32 s18, s2, 4
	v_ashrrev_i32_e32 v41, 31, v40
	v_cndmask_b32_e32 v5, v1, v5, vcc
	v_lshlrev_b32_e32 v70, 2, v5
	v_xor_b32_e32 v5, 4, v1
	v_cmp_lt_i32_e32 vcc, v5, v3
	v_mov_b32_e32 v43, 0
	v_or_b32_e32 v2, 64, v0
	v_cndmask_b32_e32 v5, v1, v5, vcc
	v_lshlrev_b32_e32 v71, 2, v5
	v_xor_b32_e32 v5, 2, v1
	v_cmp_lt_i32_e32 vcc, v5, v3
	v_or_b32_e32 v4, 0x80, v0
	v_or_b32_e32 v6, 0xc0, v0
	v_cndmask_b32_e32 v5, v1, v5, vcc
	v_lshlrev_b32_e32 v72, 2, v5
	v_xor_b32_e32 v5, 1, v1
	v_cmp_lt_i32_e32 vcc, v5, v3
	v_lshlrev_b32_e32 v42, 4, v0
	v_lshlrev_b64 v[46:47], 11, v[40:41]
	v_cndmask_b32_e32 v1, v1, v5, vcc
	s_ashr_i32 s19, s18, 31
	v_lshlrev_b64 v[48:49], 12, v[40:41]
	v_mov_b64_e32 v[50:51], s[4:5]
	s_mov_b32 s4, 0x358637bd
	v_lshlrev_b32_e32 v73, 2, v1
	v_lshl_add_u64 v[44:45], s[6:7], 0, v[42:43]
	v_lshl_or_b32 v46, v0, 3, v46
	s_lshl_b64 s[20:21], s[18:19], 11
	v_or_b32_e32 v48, v48, v42
	s_lshl_b64 s[22:23], s[18:19], 12
	s_mov_b64 s[24:25], 0
	s_movk_i32 s3, 0xfff
	s_movk_i32 s19, 0x6000
	s_mov_b64 s[26:27], 0x1000
	v_lshlrev_b32_e32 v42, 4, v0
	s_mov_b32 s29, 0x6b7b000
	s_mov_b32 s30, 0x6b7c000
	s_mov_b32 s31, 0x6b7d000
	v_lshlrev_b32_e32 v52, 4, v2
	v_mov_b32_e32 v53, v43
	v_lshlrev_b32_e32 v54, 4, v4
	v_mov_b32_e32 v55, v43
	v_lshlrev_b32_e32 v56, 4, v6
	v_mov_b32_e32 v57, v43
	s_mov_b32 s28, 0x3a800000
	v_mov_b64_e32 v[58:59], s[4:5]
	s_mov_b32 s34, 0x800000
	s_mov_b32 s35, 0x8b7a000
	s_mov_b32 s36, 0x8b7b000
	s_movk_i32 s37, 0x1fff
.LBB0_140:
	v_mov_b32_e32 v234, s64
	v_mov_b32_e32 v235, s65
	v_mov_b32_e32 v236, s66
	v_mov_b32_e32 v237, s67
	v_cmp_gt_i32_e64 s[4:5], s68, v40
	s_nop 1
	v_cndmask_b32_e64 v16, v236, v234, s[4:5]
	v_cndmask_b32_e64 v17, v237, v235, s[4:5]
	v_lshl_add_u64 v[16:17], v[16:17], 0, v[48:49]
	v_lshl_add_u64 v[4:5], s[14:15], 0, v[46:47]
	v_add_co_u32_e32 v8, vcc, 0x6b7a000, v16
	v_add_co_u32_e64 v60, s[4:5], s35, v4
	s_nop 0
	v_addc_co_u32_e32 v9, vcc, 0, v17, vcc
	v_addc_co_u32_e64 v61, s[4:5], 0, v5, s[4:5]
	v_add_u32_e32 v6, 0xfffff000, v40
	v_add_co_u32_e64 v62, s[4:5], s36, v4
	v_add_co_u32_e32 v12, vcc, s29, v16
	v_lshrrev_b32_e32 v6, 10, v6
	v_addc_co_u32_e64 v63, s[4:5], 0, v5, s[4:5]
	v_addc_co_u32_e32 v13, vcc, 0, v17, vcc
	v_add_u32_e32 v10, 1, v6
	v_cmp_lt_i32_e64 s[4:5], s3, v40
	v_add_co_u32_e32 v18, vcc, s30, v16
	global_load_dwordx4 v[0:3], v[44:45], off
	global_load_dwordx4 v[74:77], v[8:9], off offset:256
	global_load_dwordx4 v[36:39], v[8:9], off offset:1280
	global_load_dwordx4 v[20:23], v[8:9], off offset:2304
	global_load_dwordx4 v[4:7], v[8:9], off offset:3328
	v_cndmask_b32_e64 v14, 0, v10, s[4:5]
	v_addc_co_u32_e32 v19, vcc, 0, v17, vcc
	global_load_dwordx4 v[78:81], v[12:13], off offset:256
	global_load_dwordx4 v[82:85], v[12:13], off offset:1280
	global_load_dwordx4 v[24:27], v[12:13], off offset:2304
	global_load_dwordx4 v[8:11], v[12:13], off offset:3328
	v_mad_u64_u32 v[32:33], s[4:5], v14, s19, v[50:51]
	v_add_co_u32_e32 v102, vcc, s31, v16
	global_load_dwordx4 v[86:89], v[18:19], off offset:256
	global_load_dwordx4 v[90:93], v[18:19], off offset:1280
	global_load_dwordx4 v[28:31], v[18:19], off offset:2304
	global_load_dwordx4 v[12:15], v[18:19], off offset:3328
	v_lshl_add_u64 v[66:67], v[32:33], 0, s[26:27]
	v_lshl_add_u64 v[64:65], v[32:33], 0, v[42:43]
	v_addc_co_u32_e32 v103, vcc, 0, v17, vcc
	global_load_dwordx4 v[94:97], v[102:103], off offset:256
	global_load_dwordx4 v[98:101], v[102:103], off offset:1280
	global_load_dwordx4 v[32:35], v[102:103], off offset:2304
	global_load_dwordx4 v[16:19], v[102:103], off offset:3328
	v_lshl_add_u64 v[110:111], v[66:67], 0, v[42:43]
	global_load_dwordx4 v[102:105], v[64:65], off
	global_load_dwordx4 v[106:109], v[110:111], off
	v_lshl_add_u64 v[112:113], v[66:67], 0, v[52:53]
	v_add_u32_e32 v40, s18, v40
	v_lshl_add_u64 v[46:47], v[46:47], 0, s[20:21]
	v_lshl_add_u64 v[48:49], v[48:49], 0, s[22:23]
	s_waitcnt vmcnt(17)
	v_mov_b32_e32 v118, v75
	s_waitcnt vmcnt(16)
	v_mov_b32_e32 v119, v37
	v_mov_b32_e32 v116, v74
	v_mov_b32_e32 v117, v36
	s_waitcnt vmcnt(15)
	v_mov_b32_e32 v126, v21
	s_waitcnt vmcnt(14)
	v_mov_b32_e32 v127, v5
	v_pk_mul_f32 v[118:119], v[118:119], v[118:119]
	s_waitcnt vmcnt(13)
	v_mov_b32_e32 v134, v79
	s_waitcnt vmcnt(12)
	v_mov_b32_e32 v135, v83
	v_mov_b32_e32 v110, v76
	v_mov_b32_e32 v111, v38
	v_mov_b32_e32 v124, v20
	v_mov_b32_e32 v125, v4
	v_mov_b32_e32 v132, v78
	v_mov_b32_e32 v133, v82
	v_pk_mul_f32 v[126:127], v[126:127], v[126:127]
	s_waitcnt vmcnt(11)
	v_mov_b32_e32 v142, v25
	s_waitcnt vmcnt(10)
	v_mov_b32_e32 v143, v9
	v_pk_fma_f32 v[116:117], v[116:117], v[116:117], v[118:119]
	v_pk_mul_f32 v[118:119], v[134:135], v[134:135]
	s_waitcnt vmcnt(9)
	v_mov_b32_e32 v148, v87
	s_waitcnt vmcnt(8)
	v_mov_b32_e32 v149, v91
	v_mov_b32_e32 v114, v77
	v_mov_b32_e32 v115, v39
	v_mov_b32_e32 v120, v22
	v_mov_b32_e32 v121, v6
	v_mov_b32_e32 v128, v80
	v_mov_b32_e32 v129, v84
	v_mov_b32_e32 v140, v24
	v_mov_b32_e32 v141, v8
	v_mov_b32_e32 v146, v86
	v_mov_b32_e32 v147, v90
	v_pk_fma_f32 v[124:125], v[124:125], v[124:125], v[126:127]
	v_pk_mul_f32 v[126:127], v[142:143], v[142:143]
	s_waitcnt vmcnt(7)
	v_mov_b32_e32 v154, v29
	s_waitcnt vmcnt(6)
	v_mov_b32_e32 v155, v13
	v_pk_fma_f32 v[110:111], v[110:111], v[110:111], v[116:117]
	v_pk_fma_f32 v[116:117], v[132:133], v[132:133], v[118:119]
	v_pk_mul_f32 v[118:119], v[148:149], v[148:149]
	s_waitcnt vmcnt(5)
	v_mov_b32_e32 v158, v95
	s_waitcnt vmcnt(4)
	v_mov_b32_e32 v159, v99
	v_mov_b32_e32 v122, v23
	v_mov_b32_e32 v123, v7
	v_mov_b32_e32 v130, v81
	v_mov_b32_e32 v131, v85
	v_mov_b32_e32 v136, v26
	v_mov_b32_e32 v137, v10
	v_mov_b32_e32 v152, v28
	v_mov_b32_e32 v153, v12
	v_mov_b32_e32 v156, v94
	v_mov_b32_e32 v157, v98
	v_pk_fma_f32 v[120:121], v[120:121], v[120:121], v[124:125]
	v_pk_fma_f32 v[124:125], v[140:141], v[140:141], v[126:127]
	v_pk_mul_f32 v[126:127], v[154:155], v[154:155]
	s_waitcnt vmcnt(3)
	v_mov_b32_e32 v166, v33
	s_waitcnt vmcnt(2)
	v_mov_b32_e32 v167, v17
	s_waitcnt vmcnt(0)
	v_pk_add_f32 v[106:107], v[106:107], 1.0 op_sel_hi:[1,0]
	v_pk_fma_f32 v[110:111], v[114:115], v[114:115], v[110:111]
	v_pk_fma_f32 v[114:115], v[128:129], v[128:129], v[116:117]
	v_pk_fma_f32 v[116:117], v[146:147], v[146:147], v[118:119]
	v_pk_mul_f32 v[118:119], v[158:159], v[158:159]
	v_mov_b32_e32 v138, v27
	v_mov_b32_e32 v139, v11
	v_mov_b32_e32 v134, v88
	v_mov_b32_e32 v135, v92
	v_mov_b32_e32 v132, v96
	v_mov_b32_e32 v133, v100
	v_mov_b32_e32 v160, v32
	v_mov_b32_e32 v161, v16
	v_pk_add_f32 v[108:109], v[108:109], 1.0 op_sel_hi:[1,0]
	v_pk_fma_f32 v[120:121], v[122:123], v[122:123], v[120:121]
	v_pk_fma_f32 v[122:123], v[136:137], v[136:137], v[124:125]
	v_pk_fma_f32 v[124:125], v[152:153], v[152:153], v[126:127]
	v_pk_mul_f32 v[126:127], v[166:167], v[166:167]
	v_pk_mul_f32 v[0:1], v[0:1], v[106:107]
	v_pk_fma_f32 v[106:107], v[130:131], v[130:131], v[114:115]
	v_pk_fma_f32 v[114:115], v[156:157], v[156:157], v[118:119]
	v_mov_b32_e32 v144, v89
	v_mov_b32_e32 v145, v93
	v_mov_b32_e32 v142, v30
	v_mov_b32_e32 v143, v14
	v_mov_b32_e32 v148, v97
	v_mov_b32_e32 v149, v101
	v_mov_b32_e32 v140, v34
	v_mov_b32_e32 v141, v18
	v_pk_mul_f32 v[2:3], v[2:3], v[108:109]
	v_pk_fma_f32 v[108:109], v[134:135], v[134:135], v[116:117]
	v_pk_fma_f32 v[116:117], v[138:139], v[138:139], v[122:123]
	v_mov_b32_e32 v119, v110
	v_pk_fma_f32 v[126:127], v[160:161], v[160:161], v[126:127]
	v_pk_fma_f32 v[114:115], v[132:133], v[132:133], v[114:115]
	v_mov_b32_e32 v118, v106
	v_mov_b32_e32 v110, v107
	v_mov_b32_e32 v150, v31
	v_mov_b32_e32 v151, v15
	v_mov_b32_e32 v154, v35
	v_mov_b32_e32 v155, v19
	v_mov_b32_e32 v123, v120
	v_pk_fma_f32 v[124:125], v[142:143], v[142:143], v[124:125]
	v_pk_fma_f32 v[108:109], v[144:145], v[144:145], v[108:109]
	v_mov_b32_e32 v122, v116
	v_mov_b32_e32 v120, v117
	v_pk_fma_f32 v[116:117], v[140:141], v[140:141], v[126:127]
	v_pk_fma_f32 v[114:115], v[148:149], v[148:149], v[114:115]
	v_pk_add_f32 v[110:111], v[118:119], v[110:111]
	v_pk_fma_f32 v[106:107], v[150:151], v[150:151], v[124:125]
	v_pk_fma_f32 v[116:117], v[154:155], v[154:155], v[116:117]
	v_mov_b32_e32 v119, v108
	v_pk_add_f32 v[110:111], v[110:111], v[122:123]
	v_mov_b32_e32 v118, v114
	v_mov_b32_e32 v108, v115
	v_mov_b32_e32 v125, v106
	v_mov_b32_e32 v124, v116
	v_pk_add_f32 v[110:111], v[110:111], v[120:121]
	v_pk_add_f32 v[108:109], v[118:119], v[108:109]
	v_mov_b32_e32 v106, v117
	ds_bpermute_b32 v115, v68, v111
	ds_bpermute_b32 v114, v68, v110
	v_pk_add_f32 v[108:109], v[108:109], v[124:125]
	s_waitcnt lgkmcnt(0)
	v_pk_add_f32 v[110:111], v[110:111], v[114:115]
	v_pk_add_f32 v[106:107], v[108:109], v[106:107]
	ds_bpermute_b32 v109, v68, v107
	ds_bpermute_b32 v108, v68, v106
	ds_bpermute_b32 v115, v69, v111
	ds_bpermute_b32 v114, v69, v110
	s_waitcnt lgkmcnt(2)
	v_pk_add_f32 v[106:107], v[106:107], v[108:109]
	ds_bpermute_b32 v109, v69, v107
	ds_bpermute_b32 v108, v69, v106
	s_waitcnt lgkmcnt(2)
	v_pk_add_f32 v[110:111], v[110:111], v[114:115]
	ds_bpermute_b32 v115, v70, v111
	ds_bpermute_b32 v114, v70, v110
	s_waitcnt lgkmcnt(2)
	v_pk_add_f32 v[106:107], v[106:107], v[108:109]
	ds_bpermute_b32 v109, v70, v107
	ds_bpermute_b32 v108, v70, v106
	s_waitcnt lgkmcnt(2)
	v_pk_add_f32 v[110:111], v[110:111], v[114:115]
	ds_bpermute_b32 v115, v71, v111
	ds_bpermute_b32 v114, v71, v110
	s_waitcnt lgkmcnt(2)
	v_pk_add_f32 v[106:107], v[106:107], v[108:109]
	ds_bpermute_b32 v109, v71, v107
	ds_bpermute_b32 v108, v71, v106
	s_waitcnt lgkmcnt(2)
	v_pk_add_f32 v[110:111], v[110:111], v[114:115]
	ds_bpermute_b32 v115, v72, v111
	ds_bpermute_b32 v114, v72, v110
	s_waitcnt lgkmcnt(2)
	v_pk_add_f32 v[106:107], v[106:107], v[108:109]
	ds_bpermute_b32 v109, v72, v107
	ds_bpermute_b32 v108, v72, v106
	s_waitcnt lgkmcnt(2)
	v_pk_add_f32 v[110:111], v[110:111], v[114:115]
	ds_bpermute_b32 v115, v73, v111
	ds_bpermute_b32 v114, v73, v110
	s_waitcnt lgkmcnt(2)
	v_pk_add_f32 v[106:107], v[106:107], v[108:109]
	ds_bpermute_b32 v109, v73, v107
	ds_bpermute_b32 v108, v73, v106
	s_waitcnt lgkmcnt(2)
	v_pk_add_f32 v[110:111], v[110:111], v[114:115]
	s_waitcnt lgkmcnt(0)
	v_pk_add_f32 v[106:107], v[106:107], v[108:109]
	v_pk_fma_f32 v[110:111], v[110:111], s[28:29], v[58:59] op_sel_hi:[1,0,0]
	v_pk_fma_f32 v[106:107], v[106:107], s[28:29], v[58:59] op_sel_hi:[1,0,0]
	v_mul_f32_e32 v41, 0x4b800000, v111
	v_mul_f32_e32 v114, 0x4b800000, v110
	v_cmp_gt_f32_e32 vcc, s34, v110
	v_cmp_gt_f32_e64 s[4:5], s34, v111
	v_mul_f32_e32 v109, 0x4b800000, v107
	v_cndmask_b32_e32 v108, v110, v114, vcc
	v_cndmask_b32_e64 v41, v111, v41, s[4:5]
	v_rsq_f32_e32 v41, v41
	v_rsq_f32_e32 v108, v108
	v_mul_f32_e32 v110, 0x4b800000, v106
	v_cmp_gt_f32_e64 s[6:7], s34, v106
	v_cmp_gt_f32_e64 s[8:9], s34, v107
	s_nop 0
	v_cndmask_b32_e64 v106, v106, v110, s[6:7]
	v_cndmask_b32_e64 v107, v107, v109, s[8:9]
	v_rsq_f32_e32 v107, v107
	v_rsq_f32_e32 v109, v106
	v_mul_f32_e32 v106, 0x45800000, v41
	v_mul_f32_e32 v110, 0x45800000, v108
	v_cndmask_b32_e64 v106, v41, v106, s[4:5]
	v_cndmask_b32_e32 v108, v108, v110, vcc
	v_pk_mul_f32 v[74:75], v[74:75], v[106:107] op_sel_hi:[1,0]
	v_pk_mul_f32 v[76:77], v[76:77], v[106:107] op_sel_hi:[1,0]
	v_pk_mul_f32 v[78:79], v[78:79], v[108:109] op_sel_hi:[1,0]
	v_pk_mul_f32 v[80:81], v[80:81], v[108:109] op_sel_hi:[1,0]
	v_mul_f32_e32 v41, 0x45800000, v107
	v_mul_f32_e32 v111, 0x45800000, v109
	v_pk_fma_f32 v[74:75], v[74:75], v[0:1], v[102:103]
	v_pk_fma_f32 v[76:77], v[76:77], v[2:3], v[104:105]
	v_pk_fma_f32 v[78:79], v[78:79], v[0:1], v[102:103]
	v_pk_fma_f32 v[80:81], v[80:81], v[2:3], v[104:105]
	v_cndmask_b32_e64 v110, v107, v41, s[8:9]
	v_cndmask_b32_e64 v114, v109, v111, s[6:7]
	v_cvt_pk_bf16_f32 v74, v74, v75
	v_cvt_pk_bf16_f32 v75, v76, v77
	v_cvt_pk_bf16_f32 v76, v78, v79
	v_cvt_pk_bf16_f32 v77, v80, v81
	v_pk_mul_f32 v[78:79], v[86:87], v[110:111] op_sel_hi:[1,0]
	v_pk_mul_f32 v[80:81], v[88:89], v[110:111] op_sel_hi:[1,0]
	v_pk_mul_f32 v[86:87], v[94:95], v[114:115] op_sel_hi:[1,0]
	v_pk_mul_f32 v[88:89], v[96:97], v[114:115] op_sel_hi:[1,0]
	v_pk_fma_f32 v[78:79], v[78:79], v[0:1], v[102:103]
	v_pk_fma_f32 v[80:81], v[80:81], v[2:3], v[104:105]
	v_pk_fma_f32 v[0:1], v[86:87], v[0:1], v[102:103]
	v_pk_fma_f32 v[2:3], v[88:89], v[2:3], v[104:105]
	global_store_dwordx2 v[60:61], v[74:75], off offset:256
	global_store_dwordx2 v[60:61], v[76:77], off offset:2304
	v_cvt_pk_bf16_f32 v74, v78, v79
	v_cvt_pk_bf16_f32 v75, v80, v81
	v_cvt_pk_bf16_f32 v0, v0, v1
	v_cvt_pk_bf16_f32 v1, v2, v3
	global_store_dwordx2 v[62:63], v[74:75], off offset:256
	global_store_dwordx2 v[62:63], v[0:1], off offset:2304
	global_load_dwordx4 v[0:3], v[112:113], off
	s_nop 0
	global_load_dwordx4 v[74:77], v[64:65], off offset:1024
	global_load_dwordx4 v[78:81], v[44:45], off offset:1024
	v_pk_mul_f32 v[36:37], v[36:37], v[106:107] op_sel_hi:[1,0]
	v_pk_mul_f32 v[38:39], v[38:39], v[106:107] op_sel_hi:[1,0]
	v_pk_mul_f32 v[82:83], v[82:83], v[108:109] op_sel_hi:[1,0]
	v_pk_mul_f32 v[84:85], v[84:85], v[108:109] op_sel_hi:[1,0]
	v_pk_mul_f32 v[88:89], v[90:91], v[110:111] op_sel_hi:[1,0]
	v_pk_mul_f32 v[90:91], v[92:93], v[110:111] op_sel_hi:[1,0]
	v_pk_mul_f32 v[92:93], v[98:99], v[114:115] op_sel_hi:[1,0]
	v_pk_mul_f32 v[94:95], v[100:101], v[114:115] op_sel_hi:[1,0]
	v_lshl_add_u64 v[86:87], v[66:67], 0, v[54:55]
	v_pk_mul_f32 v[20:21], v[20:21], v[106:107] op_sel_hi:[1,0]
	v_pk_mul_f32 v[22:23], v[22:23], v[106:107] op_sel_hi:[1,0]
	v_pk_mul_f32 v[24:25], v[24:25], v[108:109] op_sel_hi:[1,0]
	v_pk_mul_f32 v[26:27], v[26:27], v[108:109] op_sel_hi:[1,0]
	v_pk_mul_f32 v[28:29], v[28:29], v[110:111] op_sel_hi:[1,0]
	v_pk_mul_f32 v[30:31], v[30:31], v[110:111] op_sel_hi:[1,0]
	v_pk_mul_f32 v[32:33], v[32:33], v[114:115] op_sel_hi:[1,0]
	v_pk_mul_f32 v[34:35], v[34:35], v[114:115] op_sel_hi:[1,0]
	v_lshl_add_u64 v[66:67], v[66:67], 0, v[56:57]
	v_pk_mul_f32 v[4:5], v[4:5], v[106:107] op_sel_hi:[1,0]
	v_pk_mul_f32 v[6:7], v[6:7], v[106:107] op_sel_hi:[1,0]
	v_cmp_lt_i32_e32 vcc, s37, v40
	v_pk_mul_f32 v[8:9], v[8:9], v[108:109] op_sel_hi:[1,0]
	v_pk_mul_f32 v[10:11], v[10:11], v[108:109] op_sel_hi:[1,0]
	v_pk_mul_f32 v[12:13], v[12:13], v[110:111] op_sel_hi:[1,0]
	v_pk_mul_f32 v[14:15], v[14:15], v[110:111] op_sel_hi:[1,0]
	v_pk_mul_f32 v[16:17], v[16:17], v[114:115] op_sel_hi:[1,0]
	v_pk_mul_f32 v[18:19], v[18:19], v[114:115] op_sel_hi:[1,0]
	s_or_b64 s[24:25], vcc, s[24:25]
	s_waitcnt vmcnt(2)
	v_pk_add_f32 v[0:1], v[0:1], 1.0 op_sel_hi:[1,0]
	v_pk_add_f32 v[2:3], v[2:3], 1.0 op_sel_hi:[1,0]
	s_waitcnt vmcnt(0)
	v_pk_mul_f32 v[0:1], v[78:79], v[0:1]
	v_pk_mul_f32 v[2:3], v[80:81], v[2:3]
	v_pk_fma_f32 v[36:37], v[36:37], v[0:1], v[74:75]
	v_pk_fma_f32 v[38:39], v[38:39], v[2:3], v[76:77]
	v_pk_fma_f32 v[78:79], v[82:83], v[0:1], v[74:75]
	v_pk_fma_f32 v[80:81], v[84:85], v[2:3], v[76:77]
	v_pk_fma_f32 v[82:83], v[88:89], v[0:1], v[74:75]
	v_pk_fma_f32 v[84:85], v[90:91], v[2:3], v[76:77]
	v_pk_fma_f32 v[0:1], v[92:93], v[0:1], v[74:75]
	v_pk_fma_f32 v[2:3], v[94:95], v[2:3], v[76:77]
	v_cvt_pk_bf16_f32 v36, v36, v37
	v_cvt_pk_bf16_f32 v37, v38, v39
	v_cvt_pk_bf16_f32 v38, v78, v79
	v_cvt_pk_bf16_f32 v39, v80, v81
	v_cvt_pk_bf16_f32 v74, v82, v83
	v_cvt_pk_bf16_f32 v75, v84, v85
	v_cvt_pk_bf16_f32 v0, v0, v1
	v_cvt_pk_bf16_f32 v1, v2, v3
	global_store_dwordx2 v[60:61], v[36:37], off offset:768
	global_store_dwordx2 v[60:61], v[38:39], off offset:2816
	global_store_dwordx2 v[62:63], v[74:75], off offset:768
	global_store_dwordx2 v[62:63], v[0:1], off offset:2816
	global_load_dwordx4 v[0:3], v[86:87], off
	s_nop 0
	global_load_dwordx4 v[36:39], v[64:65], off offset:2048
	global_load_dwordx4 v[74:77], v[44:45], off offset:2048
	s_waitcnt vmcnt(2)
	v_pk_add_f32 v[0:1], v[0:1], 1.0 op_sel_hi:[1,0]
	v_pk_add_f32 v[2:3], v[2:3], 1.0 op_sel_hi:[1,0]
	s_waitcnt vmcnt(0)
	v_pk_mul_f32 v[0:1], v[74:75], v[0:1]
	v_pk_mul_f32 v[2:3], v[76:77], v[2:3]
	v_pk_fma_f32 v[20:21], v[20:21], v[0:1], v[36:37]
	v_pk_fma_f32 v[22:23], v[22:23], v[2:3], v[38:39]
	v_pk_fma_f32 v[24:25], v[24:25], v[0:1], v[36:37]
	v_pk_fma_f32 v[26:27], v[26:27], v[2:3], v[38:39]
	v_pk_fma_f32 v[28:29], v[28:29], v[0:1], v[36:37]
	v_pk_fma_f32 v[30:31], v[30:31], v[2:3], v[38:39]
	v_pk_fma_f32 v[0:1], v[32:33], v[0:1], v[36:37]
	v_pk_fma_f32 v[2:3], v[34:35], v[2:3], v[38:39]
	v_cvt_pk_bf16_f32 v20, v20, v21
	v_cvt_pk_bf16_f32 v21, v22, v23
	v_cvt_pk_bf16_f32 v22, v24, v25
	v_cvt_pk_bf16_f32 v23, v26, v27
	v_cvt_pk_bf16_f32 v24, v28, v29
	v_cvt_pk_bf16_f32 v25, v30, v31
	v_cvt_pk_bf16_f32 v0, v0, v1
	v_cvt_pk_bf16_f32 v1, v2, v3
	global_store_dwordx2 v[60:61], v[20:21], off offset:1280
	global_store_dwordx2 v[60:61], v[22:23], off offset:3328
	global_store_dwordx2 v[62:63], v[24:25], off offset:1280
	global_store_dwordx2 v[62:63], v[0:1], off offset:3328
	global_load_dwordx4 v[0:3], v[66:67], off
	s_nop 0
	global_load_dwordx4 v[20:23], v[64:65], off offset:3072
	global_load_dwordx4 v[24:27], v[44:45], off offset:3072
	s_waitcnt vmcnt(2)
	v_pk_add_f32 v[0:1], v[0:1], 1.0 op_sel_hi:[1,0]
	v_pk_add_f32 v[2:3], v[2:3], 1.0 op_sel_hi:[1,0]
	s_waitcnt vmcnt(0)
	v_pk_mul_f32 v[0:1], v[24:25], v[0:1]
	v_pk_mul_f32 v[2:3], v[26:27], v[2:3]
	v_pk_fma_f32 v[4:5], v[4:5], v[0:1], v[20:21]
	v_pk_fma_f32 v[6:7], v[6:7], v[2:3], v[22:23]
	v_pk_fma_f32 v[8:9], v[8:9], v[0:1], v[20:21]
	v_pk_fma_f32 v[10:11], v[10:11], v[2:3], v[22:23]
	v_pk_fma_f32 v[12:13], v[12:13], v[0:1], v[20:21]
	v_pk_fma_f32 v[14:15], v[14:15], v[2:3], v[22:23]
	v_pk_fma_f32 v[0:1], v[16:17], v[0:1], v[20:21]
	v_pk_fma_f32 v[2:3], v[18:19], v[2:3], v[22:23]
	v_cvt_pk_bf16_f32 v4, v4, v5
	v_cvt_pk_bf16_f32 v5, v6, v7
	v_cvt_pk_bf16_f32 v6, v8, v9
	v_cvt_pk_bf16_f32 v7, v10, v11
	v_cvt_pk_bf16_f32 v8, v12, v13
	v_cvt_pk_bf16_f32 v9, v14, v15
	v_cvt_pk_bf16_f32 v0, v0, v1
	v_cvt_pk_bf16_f32 v1, v2, v3
	global_store_dwordx2 v[60:61], v[4:5], off offset:1792
	global_store_dwordx2 v[60:61], v[6:7], off offset:3840
	global_store_dwordx2 v[62:63], v[8:9], off offset:1792
	global_store_dwordx2 v[62:63], v[0:1], off offset:3840
	s_andn2_b64 exec, exec, s[24:25]
	s_cbranch_execnz .LBB0_140

.Lr6_tile:
	s_cmp_lt_u32 s15, 0x200
	s_cbranch_scc0 .Lr6_end
	s_and_b32 s2, s15, 63
	s_lshr_b32 s3, s15, 6
	s_mul_i32 s14, s2, 0x80000
	s_add_u32 s8, s26, s14
	s_addc_u32 s9, s27, 0
	s_mul_i32 s14, s3, 0x80000
	s_add_u32 s10, s28, s14
	s_addc_u32 s11, s29, 0
	s_lshl_b32 s14, s2, 19
	s_lshl_b32 s6, s3, 9
	s_add_u32 s14, s14, s6
	s_add_u32 s20, s4, 0x6b7a100
	s_addc_u32 s21, s5, 0
	s_add_u32 s20, s20, s14
	s_addc_u32 s21, s21, 0
	s_sub_u32 s7, s2, 32
	s_lshr_b32 s7, s7, 3
	s_add_u32 s7, s7, 1
	s_cmp_lt_u32 s2, 32
	s_cselect_b32 s7, 0, s7
	s_mul_i32 s7, s7, 0x6000
	s_add_u32 s7, s7, s6
	s_add_u32 s22, s4, 0x6b04000
	s_addc_u32 s23, s5, 0
	s_add_u32 s22, s22, s7
	s_addc_u32 s23, s23, 0
	v_readfirstlane_b32 s12, v247
	global_load_dword v201, v245, s[22:23] offset:0
	global_load_dword v202, v245, s[22:23] offset:64
	global_load_dword v203, v245, s[22:23] offset:128
	global_load_dword v204, v245, s[22:23] offset:192
	s_load_dwordx4 s[36:39], s[0:1], 0x0
	s_sub_u32 s7, s2, 32
	s_cmp_lt_u32 s2, 32
	s_cselect_b32 s7, s2, s7
	s_lshl_b32 s7, s7, 19
	s_add_u32 s7, s7, s6
	s_waitcnt lgkmcnt(0)
	s_cmp_lt_u32 s2, 32
	s_cselect_b32 s18, s36, s38
	s_cselect_b32 s19, s37, s39
	s_add_u32 s18, s18, s7
	s_addc_u32 s19, s19, 0
	global_load_dword v129, v246, s[18:19] offset:0
	global_load_dword v130, v246, s[18:19] offset:64
	global_load_dword v131, v246, s[18:19] offset:128
	global_load_dword v132, v246, s[18:19] offset:192
	s_add_u32 s18, s18, 0x1000
	s_addc_u32 s19, s19, 0
	global_load_dword v133, v246, s[18:19] offset:0
	global_load_dword v134, v246, s[18:19] offset:64
	global_load_dword v135, v246, s[18:19] offset:128
	global_load_dword v136, v246, s[18:19] offset:192
	s_add_u32 s18, s18, 0x1000
	s_addc_u32 s19, s19, 0
	global_load_dword v137, v246, s[18:19] offset:0
	global_load_dword v138, v246, s[18:19] offset:64
	global_load_dword v139, v246, s[18:19] offset:128
	global_load_dword v140, v246, s[18:19] offset:192
	s_add_u32 s18, s18, 0x1000
	s_addc_u32 s19, s19, 0
	global_load_dword v141, v246, s[18:19] offset:0
	global_load_dword v142, v246, s[18:19] offset:64
	global_load_dword v143, v246, s[18:19] offset:128
	global_load_dword v144, v246, s[18:19] offset:192
	s_add_u32 s18, s18, 0xd000
	s_addc_u32 s19, s19, 0
	global_load_dword v145, v246, s[18:19] offset:0
	global_load_dword v146, v246, s[18:19] offset:64
	global_load_dword v147, v246, s[18:19] offset:128
	global_load_dword v148, v246, s[18:19] offset:192
	s_add_u32 s18, s18, 0x1000
	s_addc_u32 s19, s19, 0
	global_load_dword v149, v246, s[18:19] offset:0
	global_load_dword v150, v246, s[18:19] offset:64
	global_load_dword v151, v246, s[18:19] offset:128
	global_load_dword v152, v246, s[18:19] offset:192
	s_add_u32 s18, s18, 0x1000
	s_addc_u32 s19, s19, 0
	global_load_dword v153, v246, s[18:19] offset:0
	global_load_dword v154, v246, s[18:19] offset:64
	global_load_dword v155, v246, s[18:19] offset:128
	global_load_dword v156, v246, s[18:19] offset:192
	s_add_u32 s18, s18, 0x1000
	s_addc_u32 s19, s19, 0
	global_load_dword v157, v246, s[18:19] offset:0
	global_load_dword v158, v246, s[18:19] offset:64
	global_load_dword v159, v246, s[18:19] offset:128
	global_load_dword v160, v246, s[18:19] offset:192
	s_add_u32 s18, s18, 0xd000
	s_addc_u32 s19, s19, 0
	global_load_dword v161, v246, s[18:19] offset:0
	global_load_dword v170, v246, s[18:19] offset:64
	global_load_dword v171, v246, s[18:19] offset:128
	global_load_dword v172, v246, s[18:19] offset:192
	s_add_u32 s18, s18, 0x1000
	s_addc_u32 s19, s19, 0
	global_load_dword v173, v246, s[18:19] offset:0
	global_load_dword v174, v246, s[18:19] offset:64
	global_load_dword v175, v246, s[18:19] offset:128
	global_load_dword v176, v246, s[18:19] offset:192
	s_add_u32 s18, s18, 0x1000
	s_addc_u32 s19, s19, 0
	global_load_dword v177, v246, s[18:19] offset:0
	global_load_dword v178, v246, s[18:19] offset:64
	global_load_dword v179, v246, s[18:19] offset:128
	global_load_dword v180, v246, s[18:19] offset:192
	s_add_u32 s18, s18, 0x1000
	s_addc_u32 s19, s19, 0
	global_load_dword v181, v246, s[18:19] offset:0
	global_load_dword v182, v246, s[18:19] offset:64
	global_load_dword v183, v246, s[18:19] offset:128
	global_load_dword v184, v246, s[18:19] offset:192
	s_add_u32 s18, s18, 0xd000
	s_addc_u32 s19, s19, 0
	global_load_dword v185, v246, s[18:19] offset:0
	global_load_dword v186, v246, s[18:19] offset:64
	global_load_dword v187, v246, s[18:19] offset:128
	global_load_dword v188, v246, s[18:19] offset:192
	s_add_u32 s18, s18, 0x1000
	s_addc_u32 s19, s19, 0
	global_load_dword v189, v246, s[18:19] offset:0
	global_load_dword v190, v246, s[18:19] offset:64
	global_load_dword v191, v246, s[18:19] offset:128
	global_load_dword v192, v246, s[18:19] offset:192
	s_add_u32 s18, s18, 0x1000
	s_addc_u32 s19, s19, 0
	global_load_dword v193, v246, s[18:19] offset:0
	global_load_dword v194, v246, s[18:19] offset:64
	global_load_dword v195, v246, s[18:19] offset:128
	global_load_dword v196, v246, s[18:19] offset:192
	s_add_u32 s18, s18, 0x1000
	s_addc_u32 s19, s19, 0
	global_load_dword v197, v246, s[18:19] offset:0
	global_load_dword v198, v246, s[18:19] offset:64
	global_load_dword v199, v246, s[18:19] offset:128
	global_load_dword v200, v246, s[18:19] offset:192
	s_lshl_b32 s12, s12, 12
	s_add_u32 m0, s12, 0x0
	v_mov_b32_e32 v0, 0
	global_load_lds_dwordx4 v248, s[8:9]
	v_mov_b32_e32 v1, 0
	s_add_u32 m0, s12, 0x400
	v_mov_b32_e32 v2, 0
	global_load_lds_dwordx4 v249, s[8:9]
	v_mov_b32_e32 v3, 0
	s_add_u32 m0, s12, 0x800
	v_mov_b32_e32 v4, 0
	global_load_lds_dwordx4 v250, s[8:9]
	v_mov_b32_e32 v5, 0
	s_add_u32 m0, s12, 0xc00
	v_mov_b32_e32 v6, 0
	global_load_lds_dwordx4 v251, s[8:9]
	v_mov_b32_e32 v7, 0
	s_add_u32 m0, s12, 0x8000
	v_mov_b32_e32 v8, 0
	global_load_lds_dwordx4 v248, s[10:11]
	v_mov_b32_e32 v9, 0
	s_add_u32 m0, s12, 0x8400
	v_mov_b32_e32 v10, 0
	global_load_lds_dwordx4 v249, s[10:11]
	v_mov_b32_e32 v11, 0
	s_add_u32 m0, s12, 0x8800
	v_mov_b32_e32 v12, 0
	global_load_lds_dwordx4 v250, s[10:11]
	v_mov_b32_e32 v13, 0
	s_add_u32 m0, s12, 0x8c00
	v_mov_b32_e32 v14, 0
	global_load_lds_dwordx4 v251, s[10:11]
	v_mov_b32_e32 v15, 0
	s_add_u32 s8, s8, 0x80
	s_addc_u32 s9, s9, 0
	s_add_u32 s10, s10, 0x80
	s_addc_u32 s11, s11, 0
	s_add_u32 m0, s12, 0x4000
	v_mov_b32_e32 v16, 0
	global_load_lds_dwordx4 v248, s[8:9]
	v_mov_b32_e32 v17, 0
	s_add_u32 m0, s12, 0x4400
	v_mov_b32_e32 v18, 0
	global_load_lds_dwordx4 v249, s[8:9]
	v_mov_b32_e32 v19, 0
	s_add_u32 m0, s12, 0x4800
	v_mov_b32_e32 v20, 0
	global_load_lds_dwordx4 v250, s[8:9]
	v_mov_b32_e32 v21, 0
	s_add_u32 m0, s12, 0x4c00
	v_mov_b32_e32 v22, 0
	global_load_lds_dwordx4 v251, s[8:9]
	v_mov_b32_e32 v23, 0
	s_add_u32 m0, s12, 0xc000
	v_mov_b32_e32 v24, 0
	global_load_lds_dwordx4 v248, s[10:11]
	v_mov_b32_e32 v25, 0
	s_add_u32 m0, s12, 0xc400
	v_mov_b32_e32 v26, 0
	global_load_lds_dwordx4 v249, s[10:11]
	v_mov_b32_e32 v27, 0
	s_add_u32 m0, s12, 0xc800
	v_mov_b32_e32 v28, 0
	global_load_lds_dwordx4 v250, s[10:11]
	v_mov_b32_e32 v29, 0
	s_add_u32 m0, s12, 0xcc00
	v_mov_b32_e32 v30, 0
	global_load_lds_dwordx4 v251, s[10:11]
	v_mov_b32_e32 v31, 0
	s_add_u32 s8, s8, 0x80
	s_addc_u32 s9, s9, 0
	s_add_u32 s10, s10, 0x80
	s_addc_u32 s11, s11, 0
	v_mov_b32_e32 v32, 0
	v_mov_b32_e32 v33, 0
	v_mov_b32_e32 v34, 0
	v_mov_b32_e32 v35, 0
	v_mov_b32_e32 v36, 0
	v_mov_b32_e32 v37, 0
	v_mov_b32_e32 v38, 0
	v_mov_b32_e32 v39, 0
	v_mov_b32_e32 v40, 0
	v_mov_b32_e32 v41, 0
	v_mov_b32_e32 v42, 0
	v_mov_b32_e32 v43, 0
	v_mov_b32_e32 v44, 0
	v_mov_b32_e32 v45, 0
	v_mov_b32_e32 v46, 0
	v_mov_b32_e32 v47, 0
	v_mov_b32_e32 v48, 0
	v_mov_b32_e32 v49, 0
	v_mov_b32_e32 v50, 0
	v_mov_b32_e32 v51, 0
	v_mov_b32_e32 v52, 0
	v_mov_b32_e32 v53, 0
	v_mov_b32_e32 v54, 0
	v_mov_b32_e32 v55, 0
	v_mov_b32_e32 v56, 0
	v_mov_b32_e32 v57, 0
	v_mov_b32_e32 v58, 0
	v_mov_b32_e32 v59, 0
	v_mov_b32_e32 v60, 0
	v_mov_b32_e32 v61, 0
	v_mov_b32_e32 v62, 0
	v_mov_b32_e32 v63, 0
	s_waitcnt vmcnt(8)
	s_barrier
	ds_read_b128 v[64:67], v252 offset:0
	ds_read_b128 v[96:99], v254 offset:32768
	ds_read_b128 v[100:103], v254 offset:34816
	ds_read_b128 v[104:107], v254 offset:36864
	ds_read_b128 v[108:111], v254 offset:38912
	ds_read_b128 v[68:71], v252 offset:2048
	ds_read_b128 v[72:75], v252 offset:4096
	ds_read_b128 v[76:79], v252 offset:6144
	ds_read_b128 v[80:83], v253 offset:0
	ds_read_b128 v[112:115], v255 offset:32768
	ds_read_b128 v[116:119], v255 offset:34816
	ds_read_b128 v[120:123], v255 offset:36864
	ds_read_b128 v[124:127], v255 offset:38912
	s_waitcnt lgkmcnt(11)
	v_mfma_f32_16x16x32_bf16 v[0:3], v[64:67], v[96:99], v[0:3]
	s_waitcnt lgkmcnt(10)
	v_mfma_f32_16x16x32_bf16 v[4:7], v[64:67], v[100:103], v[4:7]
	s_waitcnt lgkmcnt(9)
	v_mfma_f32_16x16x32_bf16 v[8:11], v[64:67], v[104:107], v[8:11]
	s_waitcnt lgkmcnt(8)
	v_mfma_f32_16x16x32_bf16 v[12:15], v[64:67], v[108:111], v[12:15]
	ds_read_b128 v[84:87], v253 offset:2048
	ds_read_b128 v[88:91], v253 offset:4096
	ds_read_b128 v[92:95], v253 offset:6144
	s_waitcnt lgkmcnt(10)
	v_mfma_f32_16x16x32_bf16 v[16:19], v[68:71], v[96:99], v[16:19]
	v_mfma_f32_16x16x32_bf16 v[20:23], v[68:71], v[100:103], v[20:23]
	v_mfma_f32_16x16x32_bf16 v[24:27], v[68:71], v[104:107], v[24:27]
	v_mfma_f32_16x16x32_bf16 v[28:31], v[68:71], v[108:111], v[28:31]
	s_waitcnt lgkmcnt(0)
	s_barrier
	s_add_u32 m0, s12, 0x0
	v_mfma_f32_16x16x32_bf16 v[32:35], v[72:75], v[96:99], v[32:35]
	global_load_lds_dwordx4 v248, s[8:9]
	s_add_u32 m0, s12, 0x400
	v_mfma_f32_16x16x32_bf16 v[36:39], v[72:75], v[100:103], v[36:39]
	global_load_lds_dwordx4 v249, s[8:9]
	s_add_u32 m0, s12, 0x800
	v_mfma_f32_16x16x32_bf16 v[40:43], v[72:75], v[104:107], v[40:43]
	global_load_lds_dwordx4 v250, s[8:9]
	s_add_u32 m0, s12, 0xc00
	v_mfma_f32_16x16x32_bf16 v[44:47], v[72:75], v[108:111], v[44:47]
	global_load_lds_dwordx4 v251, s[8:9]
	s_add_u32 m0, s12, 0x8000
	v_mfma_f32_16x16x32_bf16 v[48:51], v[76:79], v[96:99], v[48:51]
	global_load_lds_dwordx4 v248, s[10:11]
	s_add_u32 m0, s12, 0x8400
	v_mfma_f32_16x16x32_bf16 v[52:55], v[76:79], v[100:103], v[52:55]
	global_load_lds_dwordx4 v249, s[10:11]
	s_add_u32 m0, s12, 0x8800
	v_mfma_f32_16x16x32_bf16 v[56:59], v[76:79], v[104:107], v[56:59]
	global_load_lds_dwordx4 v250, s[10:11]
	s_add_u32 m0, s12, 0x8c00
	v_mfma_f32_16x16x32_bf16 v[60:63], v[76:79], v[108:111], v[60:63]
	global_load_lds_dwordx4 v251, s[10:11]
	s_add_u32 s8, s8, 0x80
	s_addc_u32 s9, s9, 0
	s_add_u32 s10, s10, 0x80
	s_addc_u32 s11, s11, 0
	s_waitcnt vmcnt(8)
	s_barrier
	ds_read_b128 v[64:67], v252 offset:16384
	ds_read_b128 v[96:99], v254 offset:49152
	ds_read_b128 v[100:103], v254 offset:51200
	ds_read_b128 v[104:107], v254 offset:53248
	ds_read_b128 v[108:111], v254 offset:55296
	ds_read_b128 v[68:71], v252 offset:18432
	ds_read_b128 v[72:75], v252 offset:20480
	ds_read_b128 v[76:79], v252 offset:22528
	v_mfma_f32_16x16x32_bf16 v[0:3], v[80:83], v[112:115], v[0:3]
	v_mfma_f32_16x16x32_bf16 v[4:7], v[80:83], v[116:119], v[4:7]
	v_mfma_f32_16x16x32_bf16 v[8:11], v[80:83], v[120:123], v[8:11]
	v_mfma_f32_16x16x32_bf16 v[12:15], v[80:83], v[124:127], v[12:15]
	v_mfma_f32_16x16x32_bf16 v[16:19], v[84:87], v[112:115], v[16:19]
	v_mfma_f32_16x16x32_bf16 v[20:23], v[84:87], v[116:119], v[20:23]
	v_mfma_f32_16x16x32_bf16 v[24:27], v[84:87], v[120:123], v[24:27]
	v_mfma_f32_16x16x32_bf16 v[28:31], v[84:87], v[124:127], v[28:31]
	v_mfma_f32_16x16x32_bf16 v[32:35], v[88:91], v[112:115], v[32:35]
	v_mfma_f32_16x16x32_bf16 v[36:39], v[88:91], v[116:119], v[36:39]
	v_mfma_f32_16x16x32_bf16 v[40:43], v[88:91], v[120:123], v[40:43]
	v_mfma_f32_16x16x32_bf16 v[44:47], v[88:91], v[124:127], v[44:47]
	v_mfma_f32_16x16x32_bf16 v[48:51], v[92:95], v[112:115], v[48:51]
	v_mfma_f32_16x16x32_bf16 v[52:55], v[92:95], v[116:119], v[52:55]
	v_mfma_f32_16x16x32_bf16 v[56:59], v[92:95], v[120:123], v[56:59]
	v_mfma_f32_16x16x32_bf16 v[60:63], v[92:95], v[124:127], v[60:63]
	ds_read_b128 v[80:83], v253 offset:16384
	ds_read_b128 v[112:115], v255 offset:49152
	ds_read_b128 v[116:119], v255 offset:51200
	ds_read_b128 v[120:123], v255 offset:53248
	ds_read_b128 v[124:127], v255 offset:55296
	ds_read_b128 v[84:87], v253 offset:18432
	ds_read_b128 v[88:91], v253 offset:20480
	ds_read_b128 v[92:95], v253 offset:22528
	s_waitcnt lgkmcnt(14)
	v_mfma_f32_16x16x32_bf16 v[0:3], v[64:67], v[96:99], v[0:3]
	s_waitcnt lgkmcnt(13)
	v_mfma_f32_16x16x32_bf16 v[4:7], v[64:67], v[100:103], v[4:7]
	s_waitcnt lgkmcnt(12)
	v_mfma_f32_16x16x32_bf16 v[8:11], v[64:67], v[104:107], v[8:11]
	s_waitcnt lgkmcnt(11)
	v_mfma_f32_16x16x32_bf16 v[12:15], v[64:67], v[108:111], v[12:15]
	s_waitcnt lgkmcnt(10)
	v_mfma_f32_16x16x32_bf16 v[16:19], v[68:71], v[96:99], v[16:19]
	v_mfma_f32_16x16x32_bf16 v[20:23], v[68:71], v[100:103], v[20:23]
	v_mfma_f32_16x16x32_bf16 v[24:27], v[68:71], v[104:107], v[24:27]
	v_mfma_f32_16x16x32_bf16 v[28:31], v[68:71], v[108:111], v[28:31]
	s_waitcnt lgkmcnt(0)
	s_barrier
	s_add_u32 m0, s12, 0x4000
	v_mfma_f32_16x16x32_bf16 v[32:35], v[72:75], v[96:99], v[32:35]
	global_load_lds_dwordx4 v248, s[8:9]
	s_add_u32 m0, s12, 0x4400
	v_mfma_f32_16x16x32_bf16 v[36:39], v[72:75], v[100:103], v[36:39]
	global_load_lds_dwordx4 v249, s[8:9]
	s_add_u32 m0, s12, 0x4800
	v_mfma_f32_16x16x32_bf16 v[40:43], v[72:75], v[104:107], v[40:43]
	global_load_lds_dwordx4 v250, s[8:9]
	s_add_u32 m0, s12, 0x4c00
	v_mfma_f32_16x16x32_bf16 v[44:47], v[72:75], v[108:111], v[44:47]
	global_load_lds_dwordx4 v251, s[8:9]
	s_add_u32 m0, s12, 0xc000
	v_mfma_f32_16x16x32_bf16 v[48:51], v[76:79], v[96:99], v[48:51]
	global_load_lds_dwordx4 v248, s[10:11]
	s_add_u32 m0, s12, 0xc400
	v_mfma_f32_16x16x32_bf16 v[52:55], v[76:79], v[100:103], v[52:55]
	global_load_lds_dwordx4 v249, s[10:11]
	s_add_u32 m0, s12, 0xc800
	v_mfma_f32_16x16x32_bf16 v[56:59], v[76:79], v[104:107], v[56:59]
	global_load_lds_dwordx4 v250, s[10:11]
	s_add_u32 m0, s12, 0xcc00
	v_mfma_f32_16x16x32_bf16 v[60:63], v[76:79], v[108:111], v[60:63]
	global_load_lds_dwordx4 v251, s[10:11]
	s_add_u32 s8, s8, 0x80
	s_addc_u32 s9, s9, 0
	s_add_u32 s10, s10, 0x80
	s_addc_u32 s11, s11, 0
	s_mov_b32 s13, 14
